# G4 epilogue software-pipelined: second-half G/SZ gate loads issued under first-half math as their dest quads free up (renamed dests/temps, recounted vmcnt)
# baseline (speedup 1.0000x reference)
; #define LAS __attribute__((address_space(3)))
;     __device__ __forceinline__ void epi(Acc& acc, const Unit& u, int wr, int wc, int fr, int fq, LAS unsigned char*) const {
;         f32x4 b0[2], b1[2];
; #pragma unroll
;         for (int bj = 0; bj < 2; ++bj) { const int n0 = u.pn * 256 + bj * 128 + wc * 32 + 8 * fq; b0[bj] = *(const f32x4*)(bglu + n0); b1[bj] = *(const f32x4*)(bglu + n0 + 4); }
; #pragma unroll
;         for (int ai = 0; ai < 2; ++ai) {
;             u32x4 gv[4][2], sv[4][2];
; #pragma unroll
;             for (int m = 0; m < 4; ++m) { const int tok = u.pm * 256 + ai * 128 + wr * 64 + m * 16 + fr;
; #pragma unroll
;                 for (int bj = 0; bj < 2; ++bj) { const int n0 = u.pn * 256 + bj * 128 + wc * 32 + 8 * fq;
;                     gv[m][bj] = __builtin_nontemporal_load((const u32x4*)(Gin + (size_t)(n0 >> 4) * GPLANE + (size_t)tok * 32 + (n0 & 15) * 2));
;                     sv[m][bj] = __builtin_nontemporal_load((const u32x4*)(SZ + ((((size_t)(u.pm * 8 + u.pn) * 256 + (tok & 255)) * 256) + (n0 & 255)) * 2)); } }
; #pragma unroll
.LBB0_710:
	s_lshl_b32 s18, s57, 8
	s_or_b32 s18, s18, s30
	v_or_b32_e32 v138, s18, v228
	v_readlane_b32 s76, v253, 7
	v_ashrrev_i32_e32 v139, 31, v138
	v_readlane_b32 s86, v253, 17
	v_readlane_b32 s87, v253, 18
	s_lshl_b32 s19, s72, 3
	v_lshl_add_u32 v214, s72, 8, v1
	v_lshl_add_u64 v[70:71], v[138:139], 2, s[86:87]
	global_load_dwordx4 v[74:77], v[70:71], off offset:16
	global_load_dwordx4 v[78:81], v[70:71], off
	s_add_i32 s28, s19, s57
	v_ashrrev_i32_e32 v66, 4, v138
	v_readlane_b32 s77, v253, 8
	s_ashr_i32 s29, s28, 31
	v_ashrrev_i32_e32 v67, 31, v66
	v_ashrrev_i32_e32 v215, 31, v214
	s_lshl_b64 s[76:77], s[28:29], 16
	v_lshlrev_b64 v[216:217], 20, v[66:67]
	v_lshlrev_b64 v[66:67], 5, v[214:215]
	v_lshl_add_u64 v[140:141], v[210:211], 0, v[66:67]
	v_or_b32_e32 v139, s76, v208
	v_bitop3_b32 v235, s18, v233, v228 bitop3:0xc8
	v_mov_b32_e32 v143, s77
	v_lshl_add_u64 v[66:67], v[140:141], 0, v[216:217]
	v_or_b32_e32 v142, v139, v235
	global_load_dwordx4 v[238:241], v[66:67], off nt
	v_lshl_add_u64 v[66:67], v[142:143], 1, s[22:23]
	global_load_dwordx4 v[242:245], v[66:67], off nt
	s_nop 0
	global_load_dwordx4 v[66:69], v[70:71], off offset:528
	s_nop 0
	global_load_dwordx4 v[70:73], v[70:71], off offset:512
	v_or_b32_e32 v142, 0x80, v138
	v_ashrrev_i32_e32 v144, 4, v142
	v_ashrrev_i32_e32 v145, 31, v144
	s_movk_i32 s19, 0xf8
	v_lshlrev_b64 v[218:219], 20, v[144:145]
	v_bitop3_b32 v236, v138, s19, v234 bitop3:0xc8
	v_lshl_add_u64 v[140:141], v[140:141], 0, v[218:219]
	v_or_b32_e32 v142, v139, v236
	v_lshl_add_u64 v[138:139], v[142:143], 1, s[22:23]
	global_load_dwordx4 v[198:201], v[140:141], off nt
	global_load_dwordx4 v[194:197], v[138:139], off nt
	v_or_b32_e32 v226, 16, v214
	v_ashrrev_i32_e32 v227, 31, v226
	v_lshlrev_b32_e32 v140, 8, v226
	v_lshlrev_b64 v[138:139], 5, v[226:227]
	v_and_b32_e32 v140, 0xdf00, v140
	v_lshl_add_u64 v[138:139], v[210:211], 0, v[138:139]
	v_or_b32_e32 v144, s76, v140
	v_lshl_add_u64 v[140:141], v[138:139], 0, v[216:217]
	v_or_b32_e32 v220, v144, v235
	v_mov_b32_e32 v221, s77
	v_lshl_add_u64 v[142:143], v[220:221], 1, s[22:23]
	global_load_dwordx4 v[190:193], v[140:141], off nt
	global_load_dwordx4 v[186:189], v[142:143], off nt
	v_lshl_add_u64 v[138:139], v[138:139], 0, v[218:219]
	v_or_b32_e32 v220, v144, v236
	v_lshl_add_u64 v[140:141], v[220:221], 1, s[22:23]
	global_load_dwordx4 v[182:185], v[138:139], off nt
	global_load_dwordx4 v[178:181], v[140:141], off nt
	v_or_b32_e32 v224, 32, v214
	v_ashrrev_i32_e32 v225, 31, v224
	v_lshlrev_b32_e32 v140, 8, v224
	v_lshlrev_b64 v[138:139], 5, v[224:225]
	v_and_b32_e32 v140, 0xef00, v140
	v_lshl_add_u64 v[138:139], v[210:211], 0, v[138:139]
	v_or_b32_e32 v144, s76, v140
	v_lshl_add_u64 v[140:141], v[138:139], 0, v[216:217]
	v_or_b32_e32 v220, v144, v235
	v_lshl_add_u64 v[142:143], v[220:221], 1, s[22:23]
	global_load_dwordx4 v[174:177], v[140:141], off nt
	global_load_dwordx4 v[170:173], v[142:143], off nt
	v_lshl_add_u64 v[138:139], v[138:139], 0, v[218:219]
	v_or_b32_e32 v220, v144, v236
	v_lshl_add_u64 v[140:141], v[220:221], 1, s[22:23]
	global_load_dwordx4 v[166:169], v[138:139], off nt
	global_load_dwordx4 v[162:165], v[140:141], off nt
	v_or_b32_e32 v222, 48, v214
	v_ashrrev_i32_e32 v223, 31, v222
	v_lshlrev_b32_e32 v140, 8, v222
	v_lshlrev_b64 v[138:139], 5, v[222:223]
	v_and_b32_e32 v140, 0xff00, v140
	v_lshl_add_u64 v[138:139], v[210:211], 0, v[138:139]
	v_or_b32_e32 v144, s76, v140
	v_lshl_add_u64 v[140:141], v[138:139], 0, v[216:217]
	v_or_b32_e32 v220, v144, v235
	v_lshl_add_u64 v[142:143], v[220:221], 1, s[22:23]
	global_load_dwordx4 v[158:161], v[140:141], off nt
	global_load_dwordx4 v[154:157], v[142:143], off nt
	v_or_b32_e32 v220, v144, v236
	v_lshl_add_u64 v[138:139], v[138:139], 0, v[218:219]
	v_lshl_add_u64 v[140:141], v[220:221], 1, s[22:23]
	global_load_dwordx4 v[142:145], v[138:139], off nt
	s_nop 0
	global_load_dwordx4 v[138:141], v[140:141], off nt
	s_ashr_i32 s28, s18, 6
	s_ashr_i32 s29, s28, 31
	s_lshl_b64 s[18:19], s[28:29], 22
	s_waitcnt vmcnt(0)
	v_pk_add_f32 v[148:149], v[148:149], v[76:77]
	v_pk_add_f32 v[152:153], v[152:153], v[80:81]
	v_pk_add_f32 v[150:151], v[150:151], v[78:79]
	v_pk_mul_f32 v[152:153], v[152:153], s[56:57] op_sel_hi:[1,0]
	v_pk_add_f32 v[146:147], v[146:147], v[74:75]
	v_pk_mul_f32 v[150:151], v[150:151], s[56:57] op_sel_hi:[1,0]
	v_exp_f32_e32 v152, v152
	v_exp_f32_e32 v153, v153
	v_exp_f32_e32 v150, v150
	v_exp_f32_e32 v151, v151
	v_pk_mul_f32 v[148:149], v[148:149], s[56:57] op_sel_hi:[1,0]
	v_pk_mul_f32 v[146:147], v[146:147], s[56:57] op_sel_hi:[1,0]
	v_exp_f32_e32 v148, v148
	v_exp_f32_e32 v146, v146
	v_exp_f32_e32 v149, v149
	v_exp_f32_e32 v147, v147
	v_pk_add_f32 v[152:153], v[152:153], 1.0 op_sel_hi:[1,0]
	v_pk_add_f32 v[150:151], v[150:151], 1.0 op_sel_hi:[1,0]
	v_rcp_f32_e32 v152, v152
	v_rcp_f32_e32 v153, v153
	v_pk_add_f32 v[136:137], v[136:137], v[72:73]
	v_pk_add_f32 v[134:135], v[134:135], v[70:71]
	v_pk_mul_f32 v[136:137], v[136:137], s[56:57] op_sel_hi:[1,0]
	v_pk_mul_f32 v[134:135], v[134:135], s[56:57] op_sel_hi:[1,0]
	v_rcp_f32_e32 v150, v150
	v_rcp_f32_e32 v151, v151
	v_pk_add_f32 v[148:149], v[148:149], 1.0 op_sel_hi:[1,0]
	v_pk_add_f32 v[146:147], v[146:147], 1.0 op_sel_hi:[1,0]
	v_pk_add_f32 v[132:133], v[132:133], v[68:69]
	v_pk_add_f32 v[130:131], v[130:131], v[66:67]
	v_exp_f32_e32 v134, v134
	v_exp_f32_e32 v136, v136
	v_exp_f32_e32 v137, v137
	v_exp_f32_e32 v135, v135
	v_lshlrev_b32_e32 v248, 16, v238
	v_and_b32_e32 v249, 0xffff0000, v238
	v_lshlrev_b32_e32 v238, 16, v239
	v_and_b32_e32 v239, 0xffff0000, v239
	v_lshlrev_b32_e32 v250, 16, v242
	v_and_b32_e32 v251, 0xffff0000, v242
; __device__ __forceinline__ f32x4 sigmoid4(f32x4 x) { return rcp_1p_exp2(x * -1.4426950409f); }
;     __device__ __forceinline__ void epi(Acc& acc, const Unit& u, int wr, int wc, int fr, int fq, LAS unsigned char*) const {
;     ...
;         for (int ai = 0; ai < 2; ++ai) {
;             u32x4 gv[4][2], sv[4][2];
; #pragma unroll
;             for (int m = 0; m < 4; ++m) { const int tok = u.pm * 256 + ai * 128 + wr * 64 + m * 16 + fr;
; #pragma unroll
;                 for (int bj = 0; bj < 2; ++bj) { const int n0 = u.pn * 256 + bj * 128 + wc * 32 + 8 * fq;
;                     gv[m][bj] = __builtin_nontemporal_load((const u32x4*)(Gin + (size_t)(n0 >> 4) * GPLANE + (size_t)tok * 32 + (n0 & 15) * 2));
;                     sv[m][bj] = __builtin_nontemporal_load((const u32x4*)(SZ + ((((size_t)(u.pm * 8 + u.pn) * 256 + (tok & 255)) * 256) + (n0 & 255)) * 2)); } }
; #pragma unroll
;             for (int m = 0; m < 4; ++m) { const int tok = u.pm * 256 + ai * 128 + wr * 64 + m * 16 + fr;
; #pragma unroll
;                 for (int bj = 0; bj < 2; ++bj) { const int n0 = u.pn * 256 + bj * 128 + wc * 32 + 8 * fq;
;                     const f32x4 v0 = acc[ai][bj][m][0] + b0[bj], v1 = acc[ai][bj][m][1] + b1[bj];
;                     const u32x4 gq = gv[m][bj], sq = sv[m][bj];
;                     const f32x4 o0 = bf4_lo(u32x2{gq.x, gq.y}) * bf4_lo(u32x2{sq.x, sq.y}) * sigmoid4(v0), o1 = bf4_lo(u32x2{gq.z, gq.w}) * bf4_lo(u32x2{sq.z, sq.w}) * sigmoid4(v1);
;                     u32x4 w; w.x = pk2(o0[0], o0[1]); w.y = pk2(o0[2], o0[3]); w.z = pk2(o1[0], o1[1]); w.w = pk2(o1[2], o1[3]);
;                     *(u32x4*)(A4 + (size_t)(n0 >> 6) * A4PLANE + (size_t)tok * 128 + (n0 & 63) * 2) = w; } } }
	v_lshlrev_b32_e32 v242, 16, v243
	v_and_b32_e32 v243, 0xffff0000, v243
	v_rcp_f32_e32 v146, v146
	v_rcp_f32_e32 v148, v148
	v_rcp_f32_e32 v149, v149
	v_rcp_f32_e32 v147, v147
	v_pk_mul_f32 v[132:133], v[132:133], s[56:57] op_sel_hi:[1,0]
	v_pk_mul_f32 v[130:131], v[130:131], s[56:57] op_sel_hi:[1,0]
	v_pk_mul_f32 v[238:239], v[238:239], v[242:243]
	v_exp_f32_e32 v130, v130
	v_exp_f32_e32 v132, v132
	v_exp_f32_e32 v133, v133
	v_exp_f32_e32 v131, v131
	v_pk_mul_f32 v[248:249], v[248:249], v[250:251]
	v_pk_mul_f32 v[152:153], v[238:239], v[152:153]
	v_lshlrev_b32_e32 v238, 16, v240
	v_and_b32_e32 v239, 0xffff0000, v240
	v_lshlrev_b32_e32 v240, 16, v241
	v_and_b32_e32 v241, 0xffff0000, v241
	v_lshlrev_b32_e32 v242, 16, v244
	v_and_b32_e32 v243, 0xffff0000, v244
	v_lshlrev_b32_e32 v244, 16, v245
	v_and_b32_e32 v245, 0xffff0000, v245
	s_add_u32 s72, s34, s18
	v_lshlrev_b64 v[246:247], 7, v[214:215]
	v_pk_mul_f32 v[150:151], v[248:249], v[150:151]
	v_pk_mul_f32 v[238:239], v[238:239], v[242:243]
	v_pk_mul_f32 v[240:241], v[240:241], v[244:245]
	s_addc_u32 s73, s35, s19
	v_pk_add_f32 v[136:137], v[136:137], 1.0 op_sel_hi:[1,0]
	v_pk_add_f32 v[134:135], v[134:135], 1.0 op_sel_hi:[1,0]
	v_pk_add_f32 v[128:129], v[128:129], v[80:81]
	v_pk_add_f32 v[126:127], v[126:127], v[78:79]
	v_pk_mul_f32 v[240:241], v[240:241], v[148:149]
	v_pk_mul_f32 v[148:149], v[238:239], v[146:147]
	v_cvt_pk_bf16_f32 v146, v150, v151
	v_lshl_add_u64 v[150:151], s[72:73], 0, v[246:247]
	v_rcp_f32_e32 v134, v134
	v_rcp_f32_e32 v136, v136
	v_rcp_f32_e32 v137, v137
	v_rcp_f32_e32 v135, v135
	v_pk_mul_f32 v[128:129], v[128:129], s[56:57] op_sel_hi:[1,0]
	v_pk_mul_f32 v[126:127], v[126:127], s[56:57] op_sel_hi:[1,0]
	v_cvt_pk_bf16_f32 v147, v152, v153
	v_cvt_pk_bf16_f32 v148, v148, v149
	v_cvt_pk_bf16_f32 v149, v240, v241
	v_lshl_add_u64 v[150:151], v[150:151], 0, v[206:207]
	v_pk_add_f32 v[132:133], v[132:133], 1.0 op_sel_hi:[1,0]
	v_pk_add_f32 v[130:131], v[130:131], 1.0 op_sel_hi:[1,0]
	s_or_b32 s18, s28, 2
	v_pk_add_f32 v[124:125], v[124:125], v[76:77]
	v_pk_add_f32 v[122:123], v[122:123], v[74:75]
	v_exp_f32_e32 v126, v126
	v_exp_f32_e32 v128, v128
	v_exp_f32_e32 v129, v129
	v_exp_f32_e32 v127, v127
	global_store_dwordx4 v[150:151], v[146:149], off
	v_add_u32_e32 v250, 0x80, v214
	v_ashrrev_i32_e32 v251, 31, v250
	v_lshlrev_b64 v[248:249], 5, v[250:251]
	v_lshlrev_b32_e32 v250, 8, v250
	v_lshl_add_u64 v[248:249], v[210:211], 0, v[248:249]
	v_and_b32_e32 v250, 0xcf00, v250
	v_or_b32_e32 v250, s76, v250
	v_lshl_add_u64 v[238:239], v[248:249], 0, v[216:217]
	global_load_dwordx4 v[238:241], v[238:239], off nt
	v_or_b32_e32 v220, v250, v235
	v_lshl_add_u64 v[242:243], v[220:221], 1, s[22:23]
	global_load_dwordx4 v[242:245], v[242:243], off nt
	v_lshlrev_b32_e32 v150, 16, v194
	v_and_b32_e32 v151, 0xffff0000, v194
	v_lshlrev_b32_e32 v146, 16, v198
	v_and_b32_e32 v147, 0xffff0000, v198
	v_lshlrev_b32_e32 v148, 16, v199
	v_and_b32_e32 v149, 0xffff0000, v199
	v_lshlrev_b32_e32 v152, 16, v195
	v_and_b32_e32 v153, 0xffff0000, v195
	v_rcp_f32_e32 v130, v130
	v_rcp_f32_e32 v132, v132
	v_rcp_f32_e32 v133, v133
	v_rcp_f32_e32 v131, v131
	s_ashr_i32 s19, s18, 31
	v_pk_mul_f32 v[124:125], v[124:125], s[56:57] op_sel_hi:[1,0]
	v_pk_mul_f32 v[122:123], v[122:123], s[56:57] op_sel_hi:[1,0]
	v_pk_mul_f32 v[146:147], v[146:147], v[150:151]
	v_pk_mul_f32 v[148:149], v[148:149], v[152:153]
	s_lshl_b64 s[18:19], s[18:19], 22
	v_exp_f32_e32 v122, v122
	v_exp_f32_e32 v124, v124
	v_exp_f32_e32 v125, v125
	v_exp_f32_e32 v123, v123
	v_pk_mul_f32 v[136:137], v[148:149], v[136:137]
	v_pk_mul_f32 v[134:135], v[146:147], v[134:135]
	v_lshlrev_b32_e32 v146, 16, v200
	v_and_b32_e32 v147, 0xffff0000, v200
	v_lshlrev_b32_e32 v148, 16, v201
	v_and_b32_e32 v149, 0xffff0000, v201
	v_lshlrev_b32_e32 v150, 16, v196
	v_and_b32_e32 v151, 0xffff0000, v196
	v_lshlrev_b32_e32 v152, 16, v197
	v_and_b32_e32 v153, 0xffff0000, v197
	s_add_u32 s74, s34, s18
	v_pk_mul_f32 v[146:147], v[146:147], v[150:151]
	v_pk_mul_f32 v[148:149], v[148:149], v[152:153]
	s_addc_u32 s75, s35, s19
	v_pk_add_f32 v[128:129], v[128:129], 1.0 op_sel_hi:[1,0]
	v_pk_add_f32 v[126:127], v[126:127], 1.0 op_sel_hi:[1,0]
	v_pk_add_f32 v[120:121], v[120:121], v[72:73]
	v_pk_add_f32 v[118:119], v[118:119], v[70:71]
	v_pk_mul_f32 v[148:149], v[148:149], v[132:133]
	v_pk_mul_f32 v[132:133], v[146:147], v[130:131]
	v_cvt_pk_bf16_f32 v130, v134, v135
	v_lshl_add_u64 v[134:135], s[74:75], 0, v[246:247]
	v_rcp_f32_e32 v126, v126
	v_rcp_f32_e32 v128, v128
	v_rcp_f32_e32 v129, v129
	v_rcp_f32_e32 v127, v127
	v_pk_mul_f32 v[120:121], v[120:121], s[56:57] op_sel_hi:[1,0]
	v_pk_mul_f32 v[118:119], v[118:119], s[56:57] op_sel_hi:[1,0]
	v_cvt_pk_bf16_f32 v131, v136, v137
	v_cvt_pk_bf16_f32 v132, v132, v133
	v_cvt_pk_bf16_f32 v133, v148, v149
	v_lshl_add_u64 v[134:135], v[134:135], 0, v[206:207]
	v_pk_add_f32 v[124:125], v[124:125], 1.0 op_sel_hi:[1,0]
	v_pk_add_f32 v[122:123], v[122:123], 1.0 op_sel_hi:[1,0]
	v_pk_add_f32 v[116:117], v[116:117], v[68:69]
	v_pk_add_f32 v[114:115], v[114:115], v[66:67]
	v_exp_f32_e32 v118, v118
	v_exp_f32_e32 v120, v120
	v_exp_f32_e32 v121, v121
	v_exp_f32_e32 v119, v119
	global_store_dwordx4 v[134:135], v[130:133], off
	v_lshl_add_u64 v[148:149], v[248:249], 0, v[218:219]
	global_load_dwordx4 v[148:151], v[148:149], off nt
	v_lshlrev_b32_e32 v134, 16, v191
	v_and_b32_e32 v135, 0xffff0000, v191
	v_lshlrev_b32_e32 v132, 16, v190
	v_and_b32_e32 v133, 0xffff0000, v190
	v_lshlrev_b32_e32 v136, 16, v186
	v_and_b32_e32 v137, 0xffff0000, v186
	v_lshlrev_b32_e32 v146, 16, v187
	v_and_b32_e32 v147, 0xffff0000, v187
	v_rcp_f32_e32 v122, v122
; __device__ __forceinline__ f32x4 sigmoid4(f32x4 x) { return rcp_1p_exp2(x * -1.4426950409f); }
;     __device__ __forceinline__ void epi(Acc& acc, const Unit& u, int wr, int wc, int fr, int fq, LAS unsigned char*) const {
;     ...
;         for (int ai = 0; ai < 2; ++ai) {
;             u32x4 gv[4][2], sv[4][2];
; #pragma unroll
;             for (int m = 0; m < 4; ++m) { const int tok = u.pm * 256 + ai * 128 + wr * 64 + m * 16 + fr;
; #pragma unroll
;                 for (int bj = 0; bj < 2; ++bj) { const int n0 = u.pn * 256 + bj * 128 + wc * 32 + 8 * fq;
;                     gv[m][bj] = __builtin_nontemporal_load((const u32x4*)(Gin + (size_t)(n0 >> 4) * GPLANE + (size_t)tok * 32 + (n0 & 15) * 2));
;                     sv[m][bj] = __builtin_nontemporal_load((const u32x4*)(SZ + ((((size_t)(u.pm * 8 + u.pn) * 256 + (tok & 255)) * 256) + (n0 & 255)) * 2)); } }
; #pragma unroll
;             for (int m = 0; m < 4; ++m) { const int tok = u.pm * 256 + ai * 128 + wr * 64 + m * 16 + fr;
; #pragma unroll
;                 for (int bj = 0; bj < 2; ++bj) { const int n0 = u.pn * 256 + bj * 128 + wc * 32 + 8 * fq;
;                     const f32x4 v0 = acc[ai][bj][m][0] + b0[bj], v1 = acc[ai][bj][m][1] + b1[bj];
;                     const u32x4 gq = gv[m][bj], sq = sv[m][bj];
;                     const f32x4 o0 = bf4_lo(u32x2{gq.x, gq.y}) * bf4_lo(u32x2{sq.x, sq.y}) * sigmoid4(v0), o1 = bf4_lo(u32x2{gq.z, gq.w}) * bf4_lo(u32x2{sq.z, sq.w}) * sigmoid4(v1);
;                     u32x4 w; w.x = pk2(o0[0], o0[1]); w.y = pk2(o0[2], o0[3]); w.z = pk2(o1[0], o1[1]); w.w = pk2(o1[2], o1[3]);
;                     *(u32x4*)(A4 + (size_t)(n0 >> 6) * A4PLANE + (size_t)tok * 128 + (n0 & 63) * 2) = w; } } }
	v_rcp_f32_e32 v124, v124
	v_rcp_f32_e32 v125, v125
	v_rcp_f32_e32 v123, v123
	v_pk_mul_f32 v[116:117], v[116:117], s[56:57] op_sel_hi:[1,0]
	v_pk_mul_f32 v[114:115], v[114:115], s[56:57] op_sel_hi:[1,0]
	v_pk_mul_f32 v[132:133], v[132:133], v[136:137]
	v_pk_mul_f32 v[134:135], v[134:135], v[146:147]
	v_exp_f32_e32 v114, v114
	v_exp_f32_e32 v116, v116
	v_exp_f32_e32 v117, v117
	v_exp_f32_e32 v115, v115
	v_pk_mul_f32 v[128:129], v[128:129], v[134:135]
	v_pk_mul_f32 v[126:127], v[126:127], v[132:133]
	v_lshlrev_b32_e32 v132, 16, v192
	v_and_b32_e32 v133, 0xffff0000, v192
	v_lshlrev_b32_e32 v134, 16, v193
	v_and_b32_e32 v135, 0xffff0000, v193
	v_lshlrev_b32_e32 v136, 16, v188
	v_and_b32_e32 v137, 0xffff0000, v188
	v_lshlrev_b32_e32 v146, 16, v189
	v_and_b32_e32 v147, 0xffff0000, v189
	v_lshlrev_b64 v[246:247], 7, v[226:227]
	v_pk_mul_f32 v[132:133], v[132:133], v[136:137]
	v_pk_mul_f32 v[134:135], v[134:135], v[146:147]
	v_pk_add_f32 v[120:121], v[120:121], 1.0 op_sel_hi:[1,0]
	v_pk_add_f32 v[118:119], v[118:119], 1.0 op_sel_hi:[1,0]
	v_pk_add_f32 v[112:113], v[112:113], v[80:81]
	v_pk_add_f32 v[110:111], v[110:111], v[78:79]
	v_pk_mul_f32 v[134:135], v[124:125], v[134:135]
	v_pk_mul_f32 v[124:125], v[122:123], v[132:133]
	v_cvt_pk_bf16_f32 v122, v126, v127
	v_lshl_add_u64 v[126:127], s[72:73], 0, v[246:247]
	v_rcp_f32_e32 v118, v118
	v_rcp_f32_e32 v120, v120
	v_rcp_f32_e32 v121, v121
	v_rcp_f32_e32 v119, v119
	v_pk_mul_f32 v[112:113], v[112:113], s[56:57] op_sel_hi:[1,0]
	v_pk_mul_f32 v[110:111], v[110:111], s[56:57] op_sel_hi:[1,0]
	v_cvt_pk_bf16_f32 v123, v128, v129
	v_cvt_pk_bf16_f32 v124, v124, v125
	v_cvt_pk_bf16_f32 v125, v134, v135
	v_lshl_add_u64 v[126:127], v[126:127], 0, v[206:207]
	v_pk_add_f32 v[116:117], v[116:117], 1.0 op_sel_hi:[1,0]
	v_pk_add_f32 v[114:115], v[114:115], 1.0 op_sel_hi:[1,0]
	v_pk_add_f32 v[108:109], v[108:109], v[76:77]
	v_pk_add_f32 v[106:107], v[106:107], v[74:75]
	v_exp_f32_e32 v110, v110
	v_exp_f32_e32 v112, v112
	v_exp_f32_e32 v113, v113
	v_exp_f32_e32 v111, v111
	global_store_dwordx4 v[126:127], v[122:125], off
	v_or_b32_e32 v220, v250, v236
	v_lshl_add_u64 v[130:131], v[220:221], 1, s[22:23]
	global_load_dwordx4 v[130:133], v[130:131], off nt
	v_lshlrev_b32_e32 v126, 16, v178
	v_and_b32_e32 v127, 0xffff0000, v178
	v_lshlrev_b32_e32 v122, 16, v182
	v_and_b32_e32 v123, 0xffff0000, v182
	v_lshlrev_b32_e32 v124, 16, v183
	v_and_b32_e32 v125, 0xffff0000, v183
	v_lshlrev_b32_e32 v128, 16, v179
	v_and_b32_e32 v129, 0xffff0000, v179
	v_rcp_f32_e32 v114, v114
	v_rcp_f32_e32 v116, v116
	v_rcp_f32_e32 v117, v117
	v_rcp_f32_e32 v115, v115
	v_pk_mul_f32 v[108:109], v[108:109], s[56:57] op_sel_hi:[1,0]
	v_pk_mul_f32 v[106:107], v[106:107], s[56:57] op_sel_hi:[1,0]
	v_pk_mul_f32 v[122:123], v[122:123], v[126:127]
	v_pk_mul_f32 v[124:125], v[124:125], v[128:129]
	v_exp_f32_e32 v106, v106
	v_exp_f32_e32 v108, v108
	v_exp_f32_e32 v109, v109
	v_exp_f32_e32 v107, v107
	v_pk_mul_f32 v[120:121], v[120:121], v[124:125]
	v_pk_mul_f32 v[118:119], v[118:119], v[122:123]
	v_lshlrev_b32_e32 v122, 16, v184
	v_and_b32_e32 v123, 0xffff0000, v184
	v_lshlrev_b32_e32 v124, 16, v185
	v_and_b32_e32 v125, 0xffff0000, v185
	v_lshlrev_b32_e32 v126, 16, v180
	v_and_b32_e32 v127, 0xffff0000, v180
	v_lshlrev_b32_e32 v128, 16, v181
	v_and_b32_e32 v129, 0xffff0000, v181
	v_pk_mul_f32 v[122:123], v[122:123], v[126:127]
	v_pk_mul_f32 v[124:125], v[124:125], v[128:129]
	v_pk_add_f32 v[112:113], v[112:113], 1.0 op_sel_hi:[1,0]
	v_pk_add_f32 v[110:111], v[110:111], 1.0 op_sel_hi:[1,0]
	v_pk_add_f32 v[104:105], v[104:105], v[72:73]
	v_pk_add_f32 v[102:103], v[102:103], v[70:71]
	v_pk_mul_f32 v[124:125], v[116:117], v[124:125]
	v_pk_mul_f32 v[116:117], v[114:115], v[122:123]
	v_cvt_pk_bf16_f32 v114, v118, v119
	v_lshl_add_u64 v[118:119], s[74:75], 0, v[246:247]
	v_rcp_f32_e32 v110, v110
	v_rcp_f32_e32 v112, v112
	v_rcp_f32_e32 v113, v113
	v_rcp_f32_e32 v111, v111
	v_pk_mul_f32 v[104:105], v[104:105], s[56:57] op_sel_hi:[1,0]
	v_pk_mul_f32 v[102:103], v[102:103], s[56:57] op_sel_hi:[1,0]
	v_cvt_pk_bf16_f32 v115, v120, v121
	v_cvt_pk_bf16_f32 v116, v116, v117
	v_cvt_pk_bf16_f32 v117, v124, v125
	v_lshl_add_u64 v[118:119], v[118:119], 0, v[206:207]
	v_pk_add_f32 v[108:109], v[108:109], 1.0 op_sel_hi:[1,0]
	v_pk_add_f32 v[106:107], v[106:107], 1.0 op_sel_hi:[1,0]
	v_pk_add_f32 v[100:101], v[100:101], v[68:69]
	v_pk_add_f32 v[98:99], v[98:99], v[66:67]
	v_exp_f32_e32 v102, v102
	v_exp_f32_e32 v104, v104
	v_exp_f32_e32 v105, v105
	v_exp_f32_e32 v103, v103
	global_store_dwordx4 v[118:119], v[114:117], off
	v_add_u32_e32 v250, 0x90, v214
	v_ashrrev_i32_e32 v251, 31, v250
	v_lshlrev_b64 v[248:249], 5, v[250:251]
	v_lshlrev_b32_e32 v250, 8, v250
	v_lshl_add_u64 v[248:249], v[210:211], 0, v[248:249]
	v_and_b32_e32 v250, 0xdf00, v250
	v_or_b32_e32 v250, s76, v250
	v_lshl_add_u64 v[126:127], v[248:249], 0, v[216:217]
	global_load_dwordx4 v[126:129], v[126:127], off nt
	v_lshlrev_b32_e32 v118, 16, v175
	v_and_b32_e32 v119, 0xffff0000, v175
	v_lshlrev_b32_e32 v116, 16, v174
	v_and_b32_e32 v117, 0xffff0000, v174
	v_lshlrev_b32_e32 v120, 16, v170
	v_and_b32_e32 v121, 0xffff0000, v170
	v_lshlrev_b32_e32 v122, 16, v171
	v_and_b32_e32 v123, 0xffff0000, v171
	v_rcp_f32_e32 v106, v106
	v_rcp_f32_e32 v108, v108
	v_rcp_f32_e32 v109, v109
	v_rcp_f32_e32 v107, v107
	v_pk_mul_f32 v[100:101], v[100:101], s[56:57] op_sel_hi:[1,0]
	v_pk_mul_f32 v[98:99], v[98:99], s[56:57] op_sel_hi:[1,0]
	v_pk_mul_f32 v[116:117], v[116:117], v[120:121]
	v_pk_mul_f32 v[118:119], v[118:119], v[122:123]
	v_exp_f32_e32 v98, v98
	v_exp_f32_e32 v100, v100
	v_exp_f32_e32 v101, v101
	v_exp_f32_e32 v99, v99
; __device__ __forceinline__ f32x4 sigmoid4(f32x4 x) { return rcp_1p_exp2(x * -1.4426950409f); }
;     __device__ __forceinline__ void epi(Acc& acc, const Unit& u, int wr, int wc, int fr, int fq, LAS unsigned char*) const {
;     ...
;         for (int ai = 0; ai < 2; ++ai) {
;             u32x4 gv[4][2], sv[4][2];
; #pragma unroll
;             for (int m = 0; m < 4; ++m) { const int tok = u.pm * 256 + ai * 128 + wr * 64 + m * 16 + fr;
; #pragma unroll
;                 for (int bj = 0; bj < 2; ++bj) { const int n0 = u.pn * 256 + bj * 128 + wc * 32 + 8 * fq;
;                     gv[m][bj] = __builtin_nontemporal_load((const u32x4*)(Gin + (size_t)(n0 >> 4) * GPLANE + (size_t)tok * 32 + (n0 & 15) * 2));
;                     sv[m][bj] = __builtin_nontemporal_load((const u32x4*)(SZ + ((((size_t)(u.pm * 8 + u.pn) * 256 + (tok & 255)) * 256) + (n0 & 255)) * 2)); } }
; #pragma unroll
;             for (int m = 0; m < 4; ++m) { const int tok = u.pm * 256 + ai * 128 + wr * 64 + m * 16 + fr;
; #pragma unroll
;                 for (int bj = 0; bj < 2; ++bj) { const int n0 = u.pn * 256 + bj * 128 + wc * 32 + 8 * fq;
;                     const f32x4 v0 = acc[ai][bj][m][0] + b0[bj], v1 = acc[ai][bj][m][1] + b1[bj];
;                     const u32x4 gq = gv[m][bj], sq = sv[m][bj];
;                     const f32x4 o0 = bf4_lo(u32x2{gq.x, gq.y}) * bf4_lo(u32x2{sq.x, sq.y}) * sigmoid4(v0), o1 = bf4_lo(u32x2{gq.z, gq.w}) * bf4_lo(u32x2{sq.z, sq.w}) * sigmoid4(v1);
;                     u32x4 w; w.x = pk2(o0[0], o0[1]); w.y = pk2(o0[2], o0[3]); w.z = pk2(o1[0], o1[1]); w.w = pk2(o1[2], o1[3]);
;                     *(u32x4*)(A4 + (size_t)(n0 >> 6) * A4PLANE + (size_t)tok * 128 + (n0 & 63) * 2) = w; } } }
	v_pk_mul_f32 v[112:113], v[112:113], v[118:119]
	v_pk_mul_f32 v[110:111], v[110:111], v[116:117]
	v_lshlrev_b32_e32 v116, 16, v176
	v_and_b32_e32 v117, 0xffff0000, v176
	v_lshlrev_b32_e32 v118, 16, v177
	v_and_b32_e32 v119, 0xffff0000, v177
	v_lshlrev_b32_e32 v120, 16, v172
	v_and_b32_e32 v121, 0xffff0000, v172
	v_lshlrev_b32_e32 v122, 16, v173
	v_and_b32_e32 v123, 0xffff0000, v173
	v_lshlrev_b64 v[246:247], 7, v[224:225]
	v_pk_mul_f32 v[116:117], v[116:117], v[120:121]
	v_pk_mul_f32 v[118:119], v[118:119], v[122:123]
	v_pk_add_f32 v[104:105], v[104:105], 1.0 op_sel_hi:[1,0]
	v_pk_add_f32 v[102:103], v[102:103], 1.0 op_sel_hi:[1,0]
	v_pk_add_f32 v[96:97], v[96:97], v[80:81]
	v_pk_add_f32 v[94:95], v[94:95], v[78:79]
	v_pk_mul_f32 v[118:119], v[108:109], v[118:119]
	v_pk_mul_f32 v[108:109], v[106:107], v[116:117]
	v_cvt_pk_bf16_f32 v106, v110, v111
	v_lshl_add_u64 v[110:111], s[72:73], 0, v[246:247]
	v_rcp_f32_e32 v102, v102
	v_rcp_f32_e32 v104, v104
	v_rcp_f32_e32 v105, v105
	v_rcp_f32_e32 v103, v103
	v_pk_mul_f32 v[96:97], v[96:97], s[56:57] op_sel_hi:[1,0]
	v_pk_mul_f32 v[94:95], v[94:95], s[56:57] op_sel_hi:[1,0]
	v_cvt_pk_bf16_f32 v107, v112, v113
	v_cvt_pk_bf16_f32 v108, v108, v109
	v_cvt_pk_bf16_f32 v109, v118, v119
	v_lshl_add_u64 v[110:111], v[110:111], 0, v[206:207]
	v_pk_add_f32 v[100:101], v[100:101], 1.0 op_sel_hi:[1,0]
	v_pk_add_f32 v[98:99], v[98:99], 1.0 op_sel_hi:[1,0]
	v_pk_add_f32 v[92:93], v[92:93], v[76:77]
	v_pk_add_f32 v[90:91], v[90:91], v[74:75]
	v_exp_f32_e32 v94, v94
	v_exp_f32_e32 v96, v96
	v_exp_f32_e32 v97, v97
	v_exp_f32_e32 v95, v95
	global_store_dwordx4 v[110:111], v[106:109], off
	v_or_b32_e32 v220, v250, v235
	v_lshl_add_u64 v[122:123], v[220:221], 1, s[22:23]
	global_load_dwordx4 v[122:125], v[122:123], off nt
	v_lshl_add_u64 v[118:119], v[248:249], 0, v[218:219]
	global_load_dwordx4 v[118:121], v[118:119], off nt
	v_or_b32_e32 v220, v250, v236
	v_lshl_add_u64 v[114:115], v[220:221], 1, s[22:23]
	global_load_dwordx4 v[114:117], v[114:115], off nt
	v_lshlrev_b32_e32 v110, 16, v162
	v_and_b32_e32 v111, 0xffff0000, v162
	v_lshlrev_b32_e32 v106, 16, v166
	v_and_b32_e32 v107, 0xffff0000, v166
	v_lshlrev_b32_e32 v108, 16, v167
	v_and_b32_e32 v109, 0xffff0000, v167
	v_lshlrev_b32_e32 v112, 16, v163
	v_and_b32_e32 v113, 0xffff0000, v163
	v_rcp_f32_e32 v98, v98
	v_rcp_f32_e32 v100, v100
	v_rcp_f32_e32 v101, v101
	v_rcp_f32_e32 v99, v99
	v_pk_mul_f32 v[92:93], v[92:93], s[56:57] op_sel_hi:[1,0]
	v_pk_mul_f32 v[90:91], v[90:91], s[56:57] op_sel_hi:[1,0]
	v_pk_mul_f32 v[106:107], v[106:107], v[110:111]
	v_pk_mul_f32 v[108:109], v[108:109], v[112:113]
	v_exp_f32_e32 v90, v90
	v_exp_f32_e32 v92, v92
	v_exp_f32_e32 v93, v93
	v_exp_f32_e32 v91, v91
	v_pk_mul_f32 v[104:105], v[104:105], v[108:109]
	v_pk_mul_f32 v[102:103], v[102:103], v[106:107]
	v_lshlrev_b32_e32 v106, 16, v168
	v_and_b32_e32 v107, 0xffff0000, v168
	v_lshlrev_b32_e32 v108, 16, v169
	v_and_b32_e32 v109, 0xffff0000, v169
	v_lshlrev_b32_e32 v110, 16, v164
	v_and_b32_e32 v111, 0xffff0000, v164
	v_lshlrev_b32_e32 v112, 16, v165
	v_and_b32_e32 v113, 0xffff0000, v165
	v_pk_mul_f32 v[106:107], v[106:107], v[110:111]
	v_pk_mul_f32 v[108:109], v[108:109], v[112:113]
	v_pk_add_f32 v[96:97], v[96:97], 1.0 op_sel_hi:[1,0]
	v_pk_add_f32 v[94:95], v[94:95], 1.0 op_sel_hi:[1,0]
	v_pk_add_f32 v[88:89], v[88:89], v[72:73]
	v_pk_add_f32 v[86:87], v[86:87], v[70:71]
	v_pk_mul_f32 v[108:109], v[100:101], v[108:109]
	v_pk_mul_f32 v[100:101], v[98:99], v[106:107]
	v_cvt_pk_bf16_f32 v98, v102, v103
	v_lshl_add_u64 v[102:103], s[74:75], 0, v[246:247]
	v_rcp_f32_e32 v94, v94
	v_rcp_f32_e32 v96, v96
	v_rcp_f32_e32 v97, v97
	v_rcp_f32_e32 v95, v95
	v_pk_mul_f32 v[88:89], v[88:89], s[56:57] op_sel_hi:[1,0]
	v_pk_mul_f32 v[86:87], v[86:87], s[56:57] op_sel_hi:[1,0]
	v_cvt_pk_bf16_f32 v99, v104, v105
	v_cvt_pk_bf16_f32 v100, v100, v101
	v_cvt_pk_bf16_f32 v101, v108, v109
	v_lshl_add_u64 v[102:103], v[102:103], 0, v[206:207]
	v_pk_add_f32 v[92:93], v[92:93], 1.0 op_sel_hi:[1,0]
	v_pk_add_f32 v[90:91], v[90:91], 1.0 op_sel_hi:[1,0]
	v_pk_add_f32 v[84:85], v[84:85], v[68:69]
	v_pk_add_f32 v[82:83], v[82:83], v[66:67]
	v_exp_f32_e32 v86, v86
	v_exp_f32_e32 v88, v88
	v_exp_f32_e32 v89, v89
	v_exp_f32_e32 v87, v87
	global_store_dwordx4 v[102:103], v[98:101], off
	v_add_u32_e32 v250, 0xa0, v214
	v_ashrrev_i32_e32 v251, 31, v250
	v_lshlrev_b64 v[248:249], 5, v[250:251]
	v_lshlrev_b32_e32 v250, 8, v250
	v_lshl_add_u64 v[248:249], v[210:211], 0, v[248:249]
	v_and_b32_e32 v250, 0xef00, v250
	v_or_b32_e32 v250, s76, v250
	v_lshl_add_u64 v[110:111], v[248:249], 0, v[216:217]
	global_load_dwordx4 v[110:113], v[110:111], off nt
	v_lshlrev_b32_e32 v102, 16, v159
	v_and_b32_e32 v103, 0xffff0000, v159
	v_lshlrev_b32_e32 v100, 16, v158
	v_and_b32_e32 v101, 0xffff0000, v158
	v_lshlrev_b32_e32 v104, 16, v154
	v_and_b32_e32 v105, 0xffff0000, v154
	v_lshlrev_b32_e32 v106, 16, v155
	v_and_b32_e32 v107, 0xffff0000, v155
	v_rcp_f32_e32 v90, v90
	v_rcp_f32_e32 v92, v92
	v_rcp_f32_e32 v93, v93
	v_rcp_f32_e32 v91, v91
	v_pk_mul_f32 v[84:85], v[84:85], s[56:57] op_sel_hi:[1,0]
	v_pk_mul_f32 v[82:83], v[82:83], s[56:57] op_sel_hi:[1,0]
	v_pk_mul_f32 v[100:101], v[100:101], v[104:105]
	v_pk_mul_f32 v[102:103], v[102:103], v[106:107]
	v_exp_f32_e32 v82, v82
	v_exp_f32_e32 v84, v84
	v_exp_f32_e32 v85, v85
	v_exp_f32_e32 v83, v83
	v_pk_mul_f32 v[96:97], v[96:97], v[102:103]
	v_pk_mul_f32 v[94:95], v[94:95], v[100:101]
	v_lshlrev_b32_e32 v100, 16, v160
	v_and_b32_e32 v101, 0xffff0000, v160
	v_lshlrev_b32_e32 v102, 16, v161
	v_and_b32_e32 v103, 0xffff0000, v161
	v_lshlrev_b32_e32 v104, 16, v156
	v_and_b32_e32 v105, 0xffff0000, v156
; __device__ __forceinline__ f32x4 sigmoid4(f32x4 x) { return rcp_1p_exp2(x * -1.4426950409f); }
;     __device__ __forceinline__ void epi(Acc& acc, const Unit& u, int wr, int wc, int fr, int fq, LAS unsigned char*) const {
;     ...
;         for (int ai = 0; ai < 2; ++ai) {
;             u32x4 gv[4][2], sv[4][2];
; #pragma unroll
;             for (int m = 0; m < 4; ++m) { const int tok = u.pm * 256 + ai * 128 + wr * 64 + m * 16 + fr;
; #pragma unroll
;                 for (int bj = 0; bj < 2; ++bj) { const int n0 = u.pn * 256 + bj * 128 + wc * 32 + 8 * fq;
;                     gv[m][bj] = __builtin_nontemporal_load((const u32x4*)(Gin + (size_t)(n0 >> 4) * GPLANE + (size_t)tok * 32 + (n0 & 15) * 2));
;                     sv[m][bj] = __builtin_nontemporal_load((const u32x4*)(SZ + ((((size_t)(u.pm * 8 + u.pn) * 256 + (tok & 255)) * 256) + (n0 & 255)) * 2)); } }
; #pragma unroll
;             for (int m = 0; m < 4; ++m) { const int tok = u.pm * 256 + ai * 128 + wr * 64 + m * 16 + fr;
; #pragma unroll
;                 for (int bj = 0; bj < 2; ++bj) { const int n0 = u.pn * 256 + bj * 128 + wc * 32 + 8 * fq;
;                     const f32x4 v0 = acc[ai][bj][m][0] + b0[bj], v1 = acc[ai][bj][m][1] + b1[bj];
;                     const u32x4 gq = gv[m][bj], sq = sv[m][bj];
;                     const f32x4 o0 = bf4_lo(u32x2{gq.x, gq.y}) * bf4_lo(u32x2{sq.x, sq.y}) * sigmoid4(v0), o1 = bf4_lo(u32x2{gq.z, gq.w}) * bf4_lo(u32x2{sq.z, sq.w}) * sigmoid4(v1);
;                     u32x4 w; w.x = pk2(o0[0], o0[1]); w.y = pk2(o0[2], o0[3]); w.z = pk2(o1[0], o1[1]); w.w = pk2(o1[2], o1[3]);
;                     *(u32x4*)(A4 + (size_t)(n0 >> 6) * A4PLANE + (size_t)tok * 128 + (n0 & 63) * 2) = w; } } }
	v_lshlrev_b32_e32 v106, 16, v157
	v_and_b32_e32 v107, 0xffff0000, v157
	v_lshlrev_b64 v[246:247], 7, v[222:223]
	v_pk_mul_f32 v[100:101], v[100:101], v[104:105]
	v_pk_mul_f32 v[102:103], v[102:103], v[106:107]
	v_pk_add_f32 v[88:89], v[88:89], 1.0 op_sel_hi:[1,0]
	v_pk_add_f32 v[86:87], v[86:87], 1.0 op_sel_hi:[1,0]
	v_pk_mul_f32 v[102:103], v[92:93], v[102:103]
	v_pk_mul_f32 v[92:93], v[90:91], v[100:101]
	v_cvt_pk_bf16_f32 v90, v94, v95
	v_lshl_add_u64 v[94:95], s[72:73], 0, v[246:247]
	v_rcp_f32_e32 v86, v86
	v_rcp_f32_e32 v88, v88
	v_rcp_f32_e32 v89, v89
	v_rcp_f32_e32 v87, v87
	v_cvt_pk_bf16_f32 v91, v96, v97
	v_cvt_pk_bf16_f32 v92, v92, v93
	v_cvt_pk_bf16_f32 v93, v102, v103
	v_lshl_add_u64 v[94:95], v[94:95], 0, v[206:207]
	v_pk_add_f32 v[84:85], v[84:85], 1.0 op_sel_hi:[1,0]
	v_pk_add_f32 v[82:83], v[82:83], 1.0 op_sel_hi:[1,0]
	global_store_dwordx4 v[94:95], v[90:93], off
	v_or_b32_e32 v220, v250, v235
	v_lshl_add_u64 v[106:107], v[220:221], 1, s[22:23]
	global_load_dwordx4 v[106:109], v[106:107], off nt
	v_lshl_add_u64 v[102:103], v[248:249], 0, v[218:219]
	global_load_dwordx4 v[102:105], v[102:103], off nt
	v_or_b32_e32 v220, v250, v236
	v_lshl_add_u64 v[98:99], v[220:221], 1, s[22:23]
	global_load_dwordx4 v[98:101], v[98:99], off nt
	v_lshlrev_b32_e32 v94, 16, v138
	v_and_b32_e32 v95, 0xffff0000, v138
	v_lshlrev_b32_e32 v90, 16, v142
	v_and_b32_e32 v91, 0xffff0000, v142
	v_lshlrev_b32_e32 v92, 16, v143
	v_and_b32_e32 v93, 0xffff0000, v143
	v_lshlrev_b32_e32 v96, 16, v139
	v_and_b32_e32 v97, 0xffff0000, v139
	v_rcp_f32_e32 v82, v82
	v_rcp_f32_e32 v84, v84
	v_rcp_f32_e32 v85, v85
	v_rcp_f32_e32 v83, v83
	v_pk_mul_f32 v[90:91], v[90:91], v[94:95]
	v_pk_mul_f32 v[92:93], v[92:93], v[96:97]
	v_pk_mul_f32 v[86:87], v[86:87], v[90:91]
	v_pk_mul_f32 v[88:89], v[88:89], v[92:93]
	v_lshlrev_b32_e32 v90, 16, v144
	v_and_b32_e32 v91, 0xffff0000, v144
	v_lshlrev_b32_e32 v92, 16, v145
	v_and_b32_e32 v93, 0xffff0000, v145
	v_lshlrev_b32_e32 v94, 16, v140
	v_and_b32_e32 v95, 0xffff0000, v140
	v_lshlrev_b32_e32 v96, 16, v141
	v_and_b32_e32 v97, 0xffff0000, v141
	v_pk_mul_f32 v[90:91], v[90:91], v[94:95]
	v_pk_mul_f32 v[92:93], v[92:93], v[96:97]
	v_add_u32_e32 v152, 0x80, v214
	v_pk_mul_f32 v[92:93], v[84:85], v[92:93]
	v_pk_mul_f32 v[84:85], v[82:83], v[90:91]
	v_cvt_pk_bf16_f32 v82, v86, v87
	v_lshl_add_u64 v[86:87], s[74:75], 0, v[246:247]
	v_cvt_pk_bf16_f32 v83, v88, v89
	v_cvt_pk_bf16_f32 v84, v84, v85
	v_cvt_pk_bf16_f32 v85, v92, v93
	v_lshl_add_u64 v[86:87], v[86:87], 0, v[206:207]
	global_store_dwordx4 v[86:87], v[82:85], off
	v_add_u32_e32 v250, 0xb0, v214
	v_ashrrev_i32_e32 v251, 31, v250
	v_lshlrev_b64 v[248:249], 5, v[250:251]
	v_lshlrev_b32_e32 v250, 8, v250
	v_lshl_add_u64 v[248:249], v[210:211], 0, v[248:249]
	v_and_b32_e32 v250, 0xff00, v250
	v_or_b32_e32 v250, s76, v250
	v_lshl_add_u64 v[94:95], v[248:249], 0, v[216:217]
	global_load_dwordx4 v[94:97], v[94:95], off nt
	v_or_b32_e32 v220, v250, v235
	v_lshl_add_u64 v[90:91], v[220:221], 1, s[22:23]
	global_load_dwordx4 v[90:93], v[90:91], off nt
	v_lshl_add_u64 v[86:87], v[248:249], 0, v[218:219]
	global_load_dwordx4 v[86:89], v[86:87], off nt
	v_or_b32_e32 v220, v250, v236
	v_lshl_add_u64 v[82:83], v[220:221], 1, s[22:23]
	global_load_dwordx4 v[82:85], v[82:83], off nt
	v_ashrrev_i32_e32 v153, 31, v152
	v_add_u32_e32 v138, 0x90, v214
	v_ashrrev_i32_e32 v139, 31, v138
	v_add_u32_e32 v136, 0xa0, v214
	v_ashrrev_i32_e32 v137, 31, v136
	v_add_u32_e32 v134, 0xb0, v214
	v_ashrrev_i32_e32 v135, 31, v134
	v_pk_add_f32 v[64:65], v[64:65], v[80:81]
	v_pk_add_f32 v[62:63], v[62:63], v[78:79]
	v_pk_mul_f32 v[64:65], v[64:65], s[56:57] op_sel_hi:[1,0]
	v_pk_add_f32 v[60:61], v[60:61], v[76:77]
	v_pk_add_f32 v[58:59], v[58:59], v[74:75]
	v_pk_mul_f32 v[62:63], v[62:63], s[56:57] op_sel_hi:[1,0]
	v_exp_f32_e32 v64, v64
	v_exp_f32_e32 v65, v65
	v_exp_f32_e32 v62, v62
	v_exp_f32_e32 v63, v63
	v_pk_mul_f32 v[60:61], v[60:61], s[56:57] op_sel_hi:[1,0]
	v_pk_mul_f32 v[58:59], v[58:59], s[56:57] op_sel_hi:[1,0]
	v_exp_f32_e32 v60, v60
	v_exp_f32_e32 v58, v58
	v_exp_f32_e32 v61, v61
	v_exp_f32_e32 v59, v59
	v_pk_add_f32 v[64:65], v[64:65], 1.0 op_sel_hi:[1,0]
	v_pk_add_f32 v[56:57], v[56:57], v[72:73]
	v_pk_add_f32 v[54:55], v[54:55], v[70:71]
	v_pk_add_f32 v[62:63], v[62:63], 1.0 op_sel_hi:[1,0]
	v_rcp_f32_e32 v64, v64
	v_rcp_f32_e32 v65, v65
	v_pk_mul_f32 v[56:57], v[56:57], s[56:57] op_sel_hi:[1,0]
	v_pk_mul_f32 v[54:55], v[54:55], s[56:57] op_sel_hi:[1,0]
	v_rcp_f32_e32 v62, v62
	v_rcp_f32_e32 v63, v63
	v_pk_add_f32 v[60:61], v[60:61], 1.0 op_sel_hi:[1,0]
	v_pk_add_f32 v[58:59], v[58:59], 1.0 op_sel_hi:[1,0]
	v_pk_add_f32 v[52:53], v[52:53], v[68:69]
	v_pk_add_f32 v[50:51], v[50:51], v[66:67]
	v_exp_f32_e32 v54, v54
	v_exp_f32_e32 v56, v56
	v_exp_f32_e32 v57, v57
	v_exp_f32_e32 v55, v55
	s_waitcnt vmcnt(22)
	v_lshlrev_b32_e32 v154, 16, v238
	v_and_b32_e32 v155, 0xffff0000, v238
	v_lshlrev_b32_e32 v238, 16, v239
	v_and_b32_e32 v239, 0xffff0000, v239
	s_waitcnt vmcnt(21)
; __device__ __forceinline__ f32x4 sigmoid4(f32x4 x) { return rcp_1p_exp2(x * -1.4426950409f); }
;     __device__ __forceinline__ void epi(Acc& acc, const Unit& u, int wr, int wc, int fr, int fq, LAS unsigned char*) const {
;     ...
;         for (int ai = 0; ai < 2; ++ai) {
;             u32x4 gv[4][2], sv[4][2];
; #pragma unroll
;             for (int m = 0; m < 4; ++m) { const int tok = u.pm * 256 + ai * 128 + wr * 64 + m * 16 + fr;
; #pragma unroll
;                 for (int bj = 0; bj < 2; ++bj) { const int n0 = u.pn * 256 + bj * 128 + wc * 32 + 8 * fq;
;                     gv[m][bj] = __builtin_nontemporal_load((const u32x4*)(Gin + (size_t)(n0 >> 4) * GPLANE + (size_t)tok * 32 + (n0 & 15) * 2));
;                     sv[m][bj] = __builtin_nontemporal_load((const u32x4*)(SZ + ((((size_t)(u.pm * 8 + u.pn) * 256 + (tok & 255)) * 256) + (n0 & 255)) * 2)); } }
; #pragma unroll
;             for (int m = 0; m < 4; ++m) { const int tok = u.pm * 256 + ai * 128 + wr * 64 + m * 16 + fr;
; #pragma unroll
;                 for (int bj = 0; bj < 2; ++bj) { const int n0 = u.pn * 256 + bj * 128 + wc * 32 + 8 * fq;
;                     const f32x4 v0 = acc[ai][bj][m][0] + b0[bj], v1 = acc[ai][bj][m][1] + b1[bj];
;                     const u32x4 gq = gv[m][bj], sq = sv[m][bj];
;                     const f32x4 o0 = bf4_lo(u32x2{gq.x, gq.y}) * bf4_lo(u32x2{sq.x, sq.y}) * sigmoid4(v0), o1 = bf4_lo(u32x2{gq.z, gq.w}) * bf4_lo(u32x2{sq.z, sq.w}) * sigmoid4(v1);
;                     u32x4 w; w.x = pk2(o0[0], o0[1]); w.y = pk2(o0[2], o0[3]); w.z = pk2(o1[0], o1[1]); w.w = pk2(o1[2], o1[3]);
;                     *(u32x4*)(A4 + (size_t)(n0 >> 6) * A4PLANE + (size_t)tok * 128 + (n0 & 63) * 2) = w; } } }
	v_lshlrev_b32_e32 v156, 16, v242
	v_and_b32_e32 v157, 0xffff0000, v242
	v_lshlrev_b32_e32 v242, 16, v243
	v_and_b32_e32 v243, 0xffff0000, v243
	v_rcp_f32_e32 v58, v58
	v_rcp_f32_e32 v60, v60
	v_rcp_f32_e32 v61, v61
	v_rcp_f32_e32 v59, v59
	v_pk_mul_f32 v[52:53], v[52:53], s[56:57] op_sel_hi:[1,0]
	v_pk_mul_f32 v[50:51], v[50:51], s[56:57] op_sel_hi:[1,0]
	v_pk_mul_f32 v[238:239], v[238:239], v[242:243]
	v_exp_f32_e32 v50, v50
	v_exp_f32_e32 v52, v52
	v_exp_f32_e32 v53, v53
	v_exp_f32_e32 v51, v51
	v_pk_mul_f32 v[154:155], v[154:155], v[156:157]
	v_pk_mul_f32 v[64:65], v[64:65], v[238:239]
	v_lshlrev_b32_e32 v238, 16, v240
	v_and_b32_e32 v239, 0xffff0000, v240
	v_lshlrev_b32_e32 v240, 16, v241
	v_and_b32_e32 v241, 0xffff0000, v241
	v_lshlrev_b32_e32 v242, 16, v244
	v_and_b32_e32 v243, 0xffff0000, v244
	v_lshlrev_b32_e32 v244, 16, v245
	v_and_b32_e32 v245, 0xffff0000, v245
	v_lshlrev_b64 v[152:153], 7, v[152:153]
	v_pk_mul_f32 v[62:63], v[62:63], v[154:155]
	v_pk_mul_f32 v[238:239], v[238:239], v[242:243]
	v_pk_mul_f32 v[240:241], v[240:241], v[244:245]
	v_pk_add_f32 v[56:57], v[56:57], 1.0 op_sel_hi:[1,0]
	v_pk_add_f32 v[54:55], v[54:55], 1.0 op_sel_hi:[1,0]
	v_pk_add_f32 v[48:49], v[48:49], v[80:81]
	v_pk_add_f32 v[46:47], v[46:47], v[78:79]
	v_pk_mul_f32 v[240:241], v[60:61], v[240:241]
	v_pk_mul_f32 v[60:61], v[58:59], v[238:239]
	v_cvt_pk_bf16_f32 v58, v62, v63
	v_lshl_add_u64 v[62:63], s[72:73], 0, v[152:153]
	v_rcp_f32_e32 v54, v54
	v_rcp_f32_e32 v56, v56
	v_rcp_f32_e32 v57, v57
	v_rcp_f32_e32 v55, v55
	v_pk_mul_f32 v[48:49], v[48:49], s[56:57] op_sel_hi:[1,0]
	v_pk_mul_f32 v[46:47], v[46:47], s[56:57] op_sel_hi:[1,0]
	v_cvt_pk_bf16_f32 v59, v64, v65
	v_cvt_pk_bf16_f32 v60, v60, v61
	v_cvt_pk_bf16_f32 v61, v240, v241
	v_lshl_add_u64 v[62:63], v[62:63], 0, v[206:207]
	v_pk_add_f32 v[52:53], v[52:53], 1.0 op_sel_hi:[1,0]
	v_pk_add_f32 v[50:51], v[50:51], 1.0 op_sel_hi:[1,0]
	v_pk_add_f32 v[44:45], v[44:45], v[76:77]
	v_pk_add_f32 v[42:43], v[42:43], v[74:75]
	v_exp_f32_e32 v46, v46
	v_exp_f32_e32 v48, v48
	v_exp_f32_e32 v49, v49
	v_exp_f32_e32 v47, v47
	global_store_dwordx4 v[62:63], v[58:61], off
	s_waitcnt vmcnt(18)
	v_lshlrev_b32_e32 v62, 16, v130
	v_and_b32_e32 v63, 0xffff0000, v130
	v_lshlrev_b32_e32 v58, 16, v148
	v_and_b32_e32 v59, 0xffff0000, v148
	v_lshlrev_b32_e32 v60, 16, v149
	v_and_b32_e32 v61, 0xffff0000, v149
	v_lshlrev_b32_e32 v64, 16, v131
	v_and_b32_e32 v65, 0xffff0000, v131
	v_rcp_f32_e32 v50, v50
	v_rcp_f32_e32 v52, v52
	v_rcp_f32_e32 v53, v53
	v_rcp_f32_e32 v51, v51
	v_pk_mul_f32 v[44:45], v[44:45], s[56:57] op_sel_hi:[1,0]
	v_pk_mul_f32 v[42:43], v[42:43], s[56:57] op_sel_hi:[1,0]
	v_pk_mul_f32 v[58:59], v[58:59], v[62:63]
	v_pk_mul_f32 v[60:61], v[60:61], v[64:65]
	v_exp_f32_e32 v42, v42
	v_exp_f32_e32 v44, v44
	v_exp_f32_e32 v45, v45
	v_exp_f32_e32 v43, v43
	v_pk_mul_f32 v[56:57], v[56:57], v[60:61]
	v_pk_mul_f32 v[54:55], v[54:55], v[58:59]
	v_lshlrev_b32_e32 v58, 16, v150
	v_and_b32_e32 v59, 0xffff0000, v150
	v_lshlrev_b32_e32 v60, 16, v151
	v_and_b32_e32 v61, 0xffff0000, v151
	v_lshlrev_b32_e32 v62, 16, v132
	v_and_b32_e32 v63, 0xffff0000, v132
	v_lshlrev_b32_e32 v64, 16, v133
	v_and_b32_e32 v65, 0xffff0000, v133
	v_pk_mul_f32 v[58:59], v[58:59], v[62:63]
	v_pk_mul_f32 v[60:61], v[60:61], v[64:65]
	v_pk_add_f32 v[48:49], v[48:49], 1.0 op_sel_hi:[1,0]
	v_pk_add_f32 v[46:47], v[46:47], 1.0 op_sel_hi:[1,0]
	v_pk_add_f32 v[40:41], v[40:41], v[72:73]
	v_pk_add_f32 v[38:39], v[38:39], v[70:71]
	v_pk_mul_f32 v[60:61], v[52:53], v[60:61]
	v_pk_mul_f32 v[52:53], v[50:51], v[58:59]
	v_cvt_pk_bf16_f32 v50, v54, v55
	v_lshl_add_u64 v[54:55], s[74:75], 0, v[152:153]
	v_rcp_f32_e32 v46, v46
	v_rcp_f32_e32 v48, v48
	v_rcp_f32_e32 v49, v49
	v_rcp_f32_e32 v47, v47
	v_pk_mul_f32 v[40:41], v[40:41], s[56:57] op_sel_hi:[1,0]
	v_pk_mul_f32 v[38:39], v[38:39], s[56:57] op_sel_hi:[1,0]
	v_cvt_pk_bf16_f32 v51, v56, v57
	v_cvt_pk_bf16_f32 v52, v52, v53
	v_cvt_pk_bf16_f32 v53, v60, v61
	v_lshl_add_u64 v[54:55], v[54:55], 0, v[206:207]
	v_pk_add_f32 v[44:45], v[44:45], 1.0 op_sel_hi:[1,0]
	v_pk_add_f32 v[42:43], v[42:43], 1.0 op_sel_hi:[1,0]
	v_pk_add_f32 v[36:37], v[36:37], v[68:69]
	v_pk_add_f32 v[34:35], v[34:35], v[66:67]
	v_exp_f32_e32 v38, v38
	v_exp_f32_e32 v40, v40
	v_exp_f32_e32 v41, v41
	v_exp_f32_e32 v39, v39
	global_store_dwordx4 v[54:55], v[50:53], off
	s_waitcnt vmcnt(17)
	v_lshlrev_b32_e32 v54, 16, v127
	v_and_b32_e32 v55, 0xffff0000, v127
	v_lshlrev_b32_e32 v52, 16, v126
	v_and_b32_e32 v53, 0xffff0000, v126
	s_waitcnt vmcnt(15)
	v_lshlrev_b32_e32 v56, 16, v122
	v_and_b32_e32 v57, 0xffff0000, v122
	v_lshlrev_b32_e32 v58, 16, v123
	v_and_b32_e32 v59, 0xffff0000, v123
	v_rcp_f32_e32 v42, v42
	v_rcp_f32_e32 v44, v44
	v_rcp_f32_e32 v45, v45
	v_rcp_f32_e32 v43, v43
	v_pk_mul_f32 v[36:37], v[36:37], s[56:57] op_sel_hi:[1,0]
	v_pk_mul_f32 v[34:35], v[34:35], s[56:57] op_sel_hi:[1,0]
	v_pk_mul_f32 v[52:53], v[52:53], v[56:57]
	v_pk_mul_f32 v[54:55], v[54:55], v[58:59]
	v_exp_f32_e32 v34, v34
	v_exp_f32_e32 v36, v36
	v_exp_f32_e32 v37, v37
	v_exp_f32_e32 v35, v35
	v_pk_mul_f32 v[48:49], v[48:49], v[54:55]
	v_pk_mul_f32 v[46:47], v[46:47], v[52:53]
	v_lshlrev_b32_e32 v52, 16, v128
	v_and_b32_e32 v53, 0xffff0000, v128
	v_lshlrev_b32_e32 v54, 16, v129
	v_and_b32_e32 v55, 0xffff0000, v129
	v_lshlrev_b32_e32 v56, 16, v124
	v_and_b32_e32 v57, 0xffff0000, v124
	v_lshlrev_b32_e32 v58, 16, v125
	v_and_b32_e32 v59, 0xffff0000, v125
	v_lshlrev_b64 v[50:51], 7, v[138:139]
	v_pk_mul_f32 v[52:53], v[52:53], v[56:57]
	v_pk_mul_f32 v[54:55], v[54:55], v[58:59]
	v_pk_add_f32 v[40:41], v[40:41], 1.0 op_sel_hi:[1,0]
	v_pk_add_f32 v[38:39], v[38:39], 1.0 op_sel_hi:[1,0]
	v_pk_add_f32 v[32:33], v[32:33], v[80:81]
	v_pk_add_f32 v[30:31], v[30:31], v[78:79]
	v_pk_mul_f32 v[54:55], v[44:45], v[54:55]
	v_pk_mul_f32 v[44:45], v[42:43], v[52:53]
	v_cvt_pk_bf16_f32 v42, v46, v47
	v_lshl_add_u64 v[46:47], s[72:73], 0, v[50:51]
	v_rcp_f32_e32 v38, v38
	v_rcp_f32_e32 v40, v40
	v_rcp_f32_e32 v41, v41
	v_rcp_f32_e32 v39, v39
	v_pk_mul_f32 v[32:33], v[32:33], s[56:57] op_sel_hi:[1,0]
	v_pk_mul_f32 v[30:31], v[30:31], s[56:57] op_sel_hi:[1,0]
	v_cvt_pk_bf16_f32 v43, v48, v49
	v_cvt_pk_bf16_f32 v44, v44, v45
	v_cvt_pk_bf16_f32 v45, v54, v55
	v_lshl_add_u64 v[46:47], v[46:47], 0, v[206:207]
	v_pk_add_f32 v[36:37], v[36:37], 1.0 op_sel_hi:[1,0]
	v_pk_add_f32 v[34:35], v[34:35], 1.0 op_sel_hi:[1,0]
	v_pk_add_f32 v[28:29], v[28:29], v[76:77]
	v_pk_add_f32 v[26:27], v[26:27], v[74:75]
	v_exp_f32_e32 v30, v30
	v_exp_f32_e32 v32, v32
	v_exp_f32_e32 v33, v33
	v_exp_f32_e32 v31, v31
	global_store_dwordx4 v[46:47], v[42:45], off
	s_waitcnt vmcnt(14)
; __device__ __forceinline__ f32x4 sigmoid4(f32x4 x) { return rcp_1p_exp2(x * -1.4426950409f); }
;     __device__ __forceinline__ void epi(Acc& acc, const Unit& u, int wr, int wc, int fr, int fq, LAS unsigned char*) const {
;     ...
;         for (int ai = 0; ai < 2; ++ai) {
;             u32x4 gv[4][2], sv[4][2];
; #pragma unroll
;             for (int m = 0; m < 4; ++m) { const int tok = u.pm * 256 + ai * 128 + wr * 64 + m * 16 + fr;
; #pragma unroll
;                 for (int bj = 0; bj < 2; ++bj) { const int n0 = u.pn * 256 + bj * 128 + wc * 32 + 8 * fq;
;                     gv[m][bj] = __builtin_nontemporal_load((const u32x4*)(Gin + (size_t)(n0 >> 4) * GPLANE + (size_t)tok * 32 + (n0 & 15) * 2));
;                     sv[m][bj] = __builtin_nontemporal_load((const u32x4*)(SZ + ((((size_t)(u.pm * 8 + u.pn) * 256 + (tok & 255)) * 256) + (n0 & 255)) * 2)); } }
; #pragma unroll
;             for (int m = 0; m < 4; ++m) { const int tok = u.pm * 256 + ai * 128 + wr * 64 + m * 16 + fr;
; #pragma unroll
;                 for (int bj = 0; bj < 2; ++bj) { const int n0 = u.pn * 256 + bj * 128 + wc * 32 + 8 * fq;
;                     const f32x4 v0 = acc[ai][bj][m][0] + b0[bj], v1 = acc[ai][bj][m][1] + b1[bj];
;                     const u32x4 gq = gv[m][bj], sq = sv[m][bj];
;                     const f32x4 o0 = bf4_lo(u32x2{gq.x, gq.y}) * bf4_lo(u32x2{sq.x, sq.y}) * sigmoid4(v0), o1 = bf4_lo(u32x2{gq.z, gq.w}) * bf4_lo(u32x2{sq.z, sq.w}) * sigmoid4(v1);
;                     u32x4 w; w.x = pk2(o0[0], o0[1]); w.y = pk2(o0[2], o0[3]); w.z = pk2(o1[0], o1[1]); w.w = pk2(o1[2], o1[3]);
;                     *(u32x4*)(A4 + (size_t)(n0 >> 6) * A4PLANE + (size_t)tok * 128 + (n0 & 63) * 2) = w; } } }
	v_lshlrev_b32_e32 v46, 16, v114
	v_and_b32_e32 v47, 0xffff0000, v114
	v_lshlrev_b32_e32 v42, 16, v118
	v_and_b32_e32 v43, 0xffff0000, v118
	v_lshlrev_b32_e32 v44, 16, v119
	v_and_b32_e32 v45, 0xffff0000, v119
	v_lshlrev_b32_e32 v48, 16, v115
	v_and_b32_e32 v49, 0xffff0000, v115
	v_rcp_f32_e32 v34, v34
	v_rcp_f32_e32 v36, v36
	v_rcp_f32_e32 v37, v37
	v_rcp_f32_e32 v35, v35
	v_pk_mul_f32 v[28:29], v[28:29], s[56:57] op_sel_hi:[1,0]
	v_pk_mul_f32 v[26:27], v[26:27], s[56:57] op_sel_hi:[1,0]
	v_pk_mul_f32 v[42:43], v[42:43], v[46:47]
	v_pk_mul_f32 v[44:45], v[44:45], v[48:49]
	v_exp_f32_e32 v26, v26
	v_exp_f32_e32 v28, v28
	v_exp_f32_e32 v29, v29
	v_exp_f32_e32 v27, v27
	v_pk_mul_f32 v[40:41], v[40:41], v[44:45]
	v_pk_mul_f32 v[38:39], v[38:39], v[42:43]
	v_lshlrev_b32_e32 v42, 16, v120
	v_and_b32_e32 v43, 0xffff0000, v120
	v_lshlrev_b32_e32 v44, 16, v121
	v_and_b32_e32 v45, 0xffff0000, v121
	v_lshlrev_b32_e32 v46, 16, v116
	v_and_b32_e32 v47, 0xffff0000, v116
	v_lshlrev_b32_e32 v48, 16, v117
	v_and_b32_e32 v49, 0xffff0000, v117
	v_pk_mul_f32 v[42:43], v[42:43], v[46:47]
	v_pk_mul_f32 v[44:45], v[44:45], v[48:49]
	v_pk_add_f32 v[32:33], v[32:33], 1.0 op_sel_hi:[1,0]
	v_pk_add_f32 v[30:31], v[30:31], 1.0 op_sel_hi:[1,0]
	v_pk_add_f32 v[24:25], v[24:25], v[72:73]
	v_pk_add_f32 v[22:23], v[22:23], v[70:71]
	v_pk_mul_f32 v[44:45], v[36:37], v[44:45]
	v_pk_mul_f32 v[36:37], v[34:35], v[42:43]
	v_cvt_pk_bf16_f32 v34, v38, v39
	v_lshl_add_u64 v[38:39], s[74:75], 0, v[50:51]
	v_rcp_f32_e32 v30, v30
	v_rcp_f32_e32 v32, v32
	v_rcp_f32_e32 v33, v33
	v_rcp_f32_e32 v31, v31
	v_pk_mul_f32 v[24:25], v[24:25], s[56:57] op_sel_hi:[1,0]
	v_pk_mul_f32 v[22:23], v[22:23], s[56:57] op_sel_hi:[1,0]
	v_cvt_pk_bf16_f32 v35, v40, v41
	v_cvt_pk_bf16_f32 v36, v36, v37
	v_cvt_pk_bf16_f32 v37, v44, v45
	v_lshl_add_u64 v[38:39], v[38:39], 0, v[206:207]
	v_pk_add_f32 v[28:29], v[28:29], 1.0 op_sel_hi:[1,0]
	v_pk_add_f32 v[26:27], v[26:27], 1.0 op_sel_hi:[1,0]
	v_pk_add_f32 v[20:21], v[20:21], v[68:69]
	v_pk_add_f32 v[18:19], v[18:19], v[66:67]
	v_exp_f32_e32 v22, v22
	v_exp_f32_e32 v24, v24
	v_exp_f32_e32 v25, v25
	v_exp_f32_e32 v23, v23
	global_store_dwordx4 v[38:39], v[34:37], off
	s_waitcnt vmcnt(13)
	v_lshlrev_b32_e32 v38, 16, v111
	v_and_b32_e32 v39, 0xffff0000, v111
	v_lshlrev_b32_e32 v36, 16, v110
	v_and_b32_e32 v37, 0xffff0000, v110
	s_waitcnt vmcnt(11)
	v_lshlrev_b32_e32 v40, 16, v106
	v_and_b32_e32 v41, 0xffff0000, v106
	v_lshlrev_b32_e32 v42, 16, v107
	v_and_b32_e32 v43, 0xffff0000, v107
	v_rcp_f32_e32 v26, v26
	v_rcp_f32_e32 v28, v28
	v_rcp_f32_e32 v29, v29
	v_rcp_f32_e32 v27, v27
	v_pk_mul_f32 v[20:21], v[20:21], s[56:57] op_sel_hi:[1,0]
	v_pk_mul_f32 v[18:19], v[18:19], s[56:57] op_sel_hi:[1,0]
	v_pk_mul_f32 v[36:37], v[36:37], v[40:41]
	v_pk_mul_f32 v[38:39], v[38:39], v[42:43]
	v_exp_f32_e32 v18, v18
	v_exp_f32_e32 v20, v20
	v_exp_f32_e32 v21, v21
	v_exp_f32_e32 v19, v19
	v_pk_mul_f32 v[32:33], v[32:33], v[38:39]
	v_pk_mul_f32 v[30:31], v[30:31], v[36:37]
	v_lshlrev_b32_e32 v36, 16, v112
	v_and_b32_e32 v37, 0xffff0000, v112
	v_lshlrev_b32_e32 v38, 16, v113
	v_and_b32_e32 v39, 0xffff0000, v113
	v_lshlrev_b32_e32 v40, 16, v108
	v_and_b32_e32 v41, 0xffff0000, v108
	v_lshlrev_b32_e32 v42, 16, v109
	v_and_b32_e32 v43, 0xffff0000, v109
	v_lshlrev_b64 v[34:35], 7, v[136:137]
	v_pk_mul_f32 v[36:37], v[36:37], v[40:41]
	v_pk_mul_f32 v[38:39], v[38:39], v[42:43]
	v_pk_add_f32 v[24:25], v[24:25], 1.0 op_sel_hi:[1,0]
	v_pk_add_f32 v[22:23], v[22:23], 1.0 op_sel_hi:[1,0]
	v_pk_add_f32 v[16:17], v[16:17], v[80:81]
	v_pk_add_f32 v[14:15], v[14:15], v[78:79]
	v_pk_mul_f32 v[38:39], v[28:29], v[38:39]
	v_pk_mul_f32 v[28:29], v[26:27], v[36:37]
	v_cvt_pk_bf16_f32 v26, v30, v31
	v_lshl_add_u64 v[30:31], s[72:73], 0, v[34:35]
	v_rcp_f32_e32 v22, v22
	v_rcp_f32_e32 v24, v24
	v_rcp_f32_e32 v25, v25
	v_rcp_f32_e32 v23, v23
	v_pk_mul_f32 v[16:17], v[16:17], s[56:57] op_sel_hi:[1,0]
	v_pk_mul_f32 v[14:15], v[14:15], s[56:57] op_sel_hi:[1,0]
	v_cvt_pk_bf16_f32 v27, v32, v33
	v_cvt_pk_bf16_f32 v28, v28, v29
	v_cvt_pk_bf16_f32 v29, v38, v39
	v_lshl_add_u64 v[30:31], v[30:31], 0, v[206:207]
	v_pk_add_f32 v[20:21], v[20:21], 1.0 op_sel_hi:[1,0]
	v_pk_add_f32 v[18:19], v[18:19], 1.0 op_sel_hi:[1,0]
	v_pk_add_f32 v[12:13], v[12:13], v[76:77]
	v_pk_add_f32 v[10:11], v[10:11], v[74:75]
	v_exp_f32_e32 v14, v14
	v_exp_f32_e32 v16, v16
	v_exp_f32_e32 v17, v17
	v_exp_f32_e32 v15, v15
	global_store_dwordx4 v[30:31], v[26:29], off
	s_waitcnt vmcnt(10)
; __device__ __forceinline__ f32x4 sigmoid4(f32x4 x) { return rcp_1p_exp2(x * -1.4426950409f); }
; #define G8_BAR __builtin_amdgcn_s_barrier()
; template <class P>
; __device__ __forceinline__ void gemm_phase(LAS unsigned char* lds, const P& p, const int G, const int c) {
;     ...
;         if (wr == 0) G8_BAR;
;         p.epi(acc, cur, wr, wc, fr, fq, lds);
;         if (!has_next) break;
; #pragma unroll
;         for (int a = 0; a < 2; ++a)
; #pragma unroll
;             for (int b = 0; b < 2; ++b)
; #pragma unroll
;                 for (int m = 0; m < 4; ++m)
; #pragma unroll
;                     for (int n = 0; n < 2; ++n) acc[a][b][m][n] = (f32x4){0.f, 0.f, 0.f, 0.f};
;         cur = nxt; ++ui; cA0 = nA0; cA1 = nA1; cB0 = nB0; cB1 = nB1;
;         if (wr == 1) G8_BAR;
;     __device__ __forceinline__ void epi(Acc& acc, const Unit& u, int wr, int wc, int fr, int fq, LAS unsigned char*) const {
;     ...
;             for (int m = 0; m < 4; ++m) { const int tok = u.pm * 256 + ai * 128 + wr * 64 + m * 16 + fr;
; #pragma unroll
;                 for (int bj = 0; bj < 2; ++bj) { const int n0 = u.pn * 256 + bj * 128 + wc * 32 + 8 * fq;
;                     const f32x4 v0 = acc[ai][bj][m][0] + b0[bj], v1 = acc[ai][bj][m][1] + b1[bj];
;                     const u32x4 gq = gv[m][bj], sq = sv[m][bj];
;                     const f32x4 o0 = bf4_lo(u32x2{gq.x, gq.y}) * bf4_lo(u32x2{sq.x, sq.y}) * sigmoid4(v0), o1 = bf4_lo(u32x2{gq.z, gq.w}) * bf4_lo(u32x2{sq.z, sq.w}) * sigmoid4(v1);
;                     u32x4 w; w.x = pk2(o0[0], o0[1]); w.y = pk2(o0[2], o0[3]); w.z = pk2(o1[0], o1[1]); w.w = pk2(o1[2], o1[3]);
;                     *(u32x4*)(A4 + (size_t)(n0 >> 6) * A4PLANE + (size_t)tok * 128 + (n0 & 63) * 2) = w; } } }
	v_lshlrev_b32_e32 v30, 16, v98
	v_and_b32_e32 v31, 0xffff0000, v98
	v_lshlrev_b32_e32 v26, 16, v102
	v_and_b32_e32 v27, 0xffff0000, v102
	v_lshlrev_b32_e32 v28, 16, v103
	v_and_b32_e32 v29, 0xffff0000, v103
	v_lshlrev_b32_e32 v32, 16, v99
	v_and_b32_e32 v33, 0xffff0000, v99
	v_rcp_f32_e32 v18, v18
	v_rcp_f32_e32 v20, v20
	v_rcp_f32_e32 v21, v21
	v_rcp_f32_e32 v19, v19
	v_pk_mul_f32 v[12:13], v[12:13], s[56:57] op_sel_hi:[1,0]
	v_pk_mul_f32 v[10:11], v[10:11], s[56:57] op_sel_hi:[1,0]
	v_pk_mul_f32 v[26:27], v[26:27], v[30:31]
	v_pk_mul_f32 v[28:29], v[28:29], v[32:33]
	v_exp_f32_e32 v10, v10
	v_exp_f32_e32 v12, v12
	v_exp_f32_e32 v13, v13
	v_exp_f32_e32 v11, v11
	v_pk_mul_f32 v[24:25], v[24:25], v[28:29]
	v_pk_mul_f32 v[22:23], v[22:23], v[26:27]
	v_lshlrev_b32_e32 v26, 16, v104
	v_and_b32_e32 v27, 0xffff0000, v104
	v_lshlrev_b32_e32 v28, 16, v105
	v_and_b32_e32 v29, 0xffff0000, v105
	v_lshlrev_b32_e32 v30, 16, v100
	v_and_b32_e32 v31, 0xffff0000, v100
	v_lshlrev_b32_e32 v32, 16, v101
	v_and_b32_e32 v33, 0xffff0000, v101
	v_pk_mul_f32 v[26:27], v[26:27], v[30:31]
	v_pk_mul_f32 v[28:29], v[28:29], v[32:33]
	v_pk_add_f32 v[16:17], v[16:17], 1.0 op_sel_hi:[1,0]
	v_pk_add_f32 v[14:15], v[14:15], 1.0 op_sel_hi:[1,0]
	v_pk_add_f32 v[8:9], v[8:9], v[72:73]
	v_pk_add_f32 v[6:7], v[6:7], v[70:71]
	v_pk_mul_f32 v[28:29], v[20:21], v[28:29]
	v_pk_mul_f32 v[20:21], v[18:19], v[26:27]
	v_cvt_pk_bf16_f32 v18, v22, v23
	v_lshl_add_u64 v[22:23], s[74:75], 0, v[34:35]
	v_rcp_f32_e32 v14, v14
	v_rcp_f32_e32 v16, v16
	v_rcp_f32_e32 v17, v17
	v_rcp_f32_e32 v15, v15
	v_pk_mul_f32 v[8:9], v[8:9], s[56:57] op_sel_hi:[1,0]
	v_pk_mul_f32 v[6:7], v[6:7], s[56:57] op_sel_hi:[1,0]
	v_cvt_pk_bf16_f32 v19, v24, v25
	v_cvt_pk_bf16_f32 v20, v20, v21
	v_cvt_pk_bf16_f32 v21, v28, v29
	v_lshl_add_u64 v[22:23], v[22:23], 0, v[206:207]
	v_pk_add_f32 v[12:13], v[12:13], 1.0 op_sel_hi:[1,0]
	v_pk_add_f32 v[10:11], v[10:11], 1.0 op_sel_hi:[1,0]
	v_pk_add_f32 v[4:5], v[4:5], v[68:69]
	v_pk_add_f32 v[2:3], v[2:3], v[66:67]
	v_exp_f32_e32 v6, v6
	v_exp_f32_e32 v8, v8
	v_exp_f32_e32 v9, v9
	v_exp_f32_e32 v7, v7
	global_store_dwordx4 v[22:23], v[18:21], off
	s_waitcnt vmcnt(9)
	v_lshlrev_b32_e32 v22, 16, v95
	v_and_b32_e32 v23, 0xffff0000, v95
	v_lshlrev_b32_e32 v20, 16, v94
	v_and_b32_e32 v21, 0xffff0000, v94
	s_waitcnt vmcnt(8)
	v_lshlrev_b32_e32 v24, 16, v90
	v_and_b32_e32 v25, 0xffff0000, v90
	v_lshlrev_b32_e32 v26, 16, v91
	v_and_b32_e32 v27, 0xffff0000, v91
	v_rcp_f32_e32 v10, v10
	v_rcp_f32_e32 v12, v12
	v_rcp_f32_e32 v13, v13
	v_rcp_f32_e32 v11, v11
	v_pk_mul_f32 v[4:5], v[4:5], s[56:57] op_sel_hi:[1,0]
	v_pk_mul_f32 v[2:3], v[2:3], s[56:57] op_sel_hi:[1,0]
	v_pk_mul_f32 v[20:21], v[20:21], v[24:25]
	v_pk_mul_f32 v[22:23], v[22:23], v[26:27]
	v_exp_f32_e32 v2, v2
	v_exp_f32_e32 v4, v4
	v_exp_f32_e32 v5, v5
	v_exp_f32_e32 v3, v3
	v_pk_mul_f32 v[16:17], v[16:17], v[22:23]
	v_pk_mul_f32 v[14:15], v[14:15], v[20:21]
	v_lshlrev_b32_e32 v20, 16, v96
	v_and_b32_e32 v21, 0xffff0000, v96
	v_lshlrev_b32_e32 v22, 16, v97
	v_and_b32_e32 v23, 0xffff0000, v97
	v_lshlrev_b32_e32 v24, 16, v92
	v_and_b32_e32 v25, 0xffff0000, v92
	v_lshlrev_b32_e32 v26, 16, v93
	v_and_b32_e32 v27, 0xffff0000, v93
	v_lshlrev_b64 v[18:19], 7, v[134:135]
	v_pk_mul_f32 v[20:21], v[20:21], v[24:25]
	v_pk_mul_f32 v[22:23], v[22:23], v[26:27]
	v_pk_add_f32 v[8:9], v[8:9], 1.0 op_sel_hi:[1,0]
	v_pk_add_f32 v[6:7], v[6:7], 1.0 op_sel_hi:[1,0]
	v_pk_mul_f32 v[22:23], v[12:13], v[22:23]
	v_pk_mul_f32 v[12:13], v[10:11], v[20:21]
	v_cvt_pk_bf16_f32 v10, v14, v15
	v_lshl_add_u64 v[14:15], s[72:73], 0, v[18:19]
	v_rcp_f32_e32 v6, v6
	v_rcp_f32_e32 v8, v8
	v_rcp_f32_e32 v9, v9
	v_rcp_f32_e32 v7, v7
	v_cvt_pk_bf16_f32 v11, v16, v17
	v_cvt_pk_bf16_f32 v12, v12, v13
	v_cvt_pk_bf16_f32 v13, v22, v23
	v_lshl_add_u64 v[14:15], v[14:15], 0, v[206:207]
	v_pk_add_f32 v[4:5], v[4:5], 1.0 op_sel_hi:[1,0]
	v_pk_add_f32 v[2:3], v[2:3], 1.0 op_sel_hi:[1,0]
	global_store_dwordx4 v[14:15], v[10:13], off
	s_waitcnt vmcnt(7)
	v_lshlrev_b32_e32 v14, 16, v82
	v_and_b32_e32 v15, 0xffff0000, v82
	v_lshlrev_b32_e32 v10, 16, v86
	v_and_b32_e32 v11, 0xffff0000, v86
	v_lshlrev_b32_e32 v12, 16, v87
	v_and_b32_e32 v13, 0xffff0000, v87
	v_lshlrev_b32_e32 v16, 16, v83
	v_and_b32_e32 v17, 0xffff0000, v83
	v_rcp_f32_e32 v2, v2
	v_rcp_f32_e32 v4, v4
	v_rcp_f32_e32 v5, v5
	v_rcp_f32_e32 v3, v3
	v_pk_mul_f32 v[10:11], v[10:11], v[14:15]
	v_pk_mul_f32 v[12:13], v[12:13], v[16:17]
	v_pk_mul_f32 v[6:7], v[6:7], v[10:11]
	v_pk_mul_f32 v[8:9], v[8:9], v[12:13]
	v_lshlrev_b32_e32 v10, 16, v88
	v_and_b32_e32 v11, 0xffff0000, v88
	v_lshlrev_b32_e32 v12, 16, v89
	v_and_b32_e32 v13, 0xffff0000, v89
	v_lshlrev_b32_e32 v14, 16, v84
	v_and_b32_e32 v15, 0xffff0000, v84
	v_lshlrev_b32_e32 v16, 16, v85
	v_and_b32_e32 v17, 0xffff0000, v85
	v_pk_mul_f32 v[10:11], v[10:11], v[14:15]
	v_pk_mul_f32 v[12:13], v[12:13], v[16:17]
	v_readlane_b32 s84, v253, 15
	v_pk_mul_f32 v[12:13], v[4:5], v[12:13]
	v_pk_mul_f32 v[4:5], v[2:3], v[10:11]
	v_cvt_pk_bf16_f32 v2, v6, v7
	v_lshl_add_u64 v[6:7], s[74:75], 0, v[18:19]
	v_cvt_pk_bf16_f32 v3, v8, v9
	v_cvt_pk_bf16_f32 v4, v4, v5
	v_cvt_pk_bf16_f32 v5, v12, v13
	v_lshl_add_u64 v[6:7], v[6:7], 0, v[206:207]
	s_andn2_b64 vcc, exec, s[58:59]
	s_mov_b64 s[18:19], -1
	v_readlane_b32 s84, v253, 44
	v_readlane_b32 s78, v253, 9
	v_readlane_b32 s79, v253, 10
	v_readlane_b32 s80, v253, 11
	v_readlane_b32 s81, v253, 12
	v_readlane_b32 s82, v253, 13
	v_readlane_b32 s83, v253, 14
	v_readlane_b32 s85, v253, 16
	v_readlane_b32 s88, v253, 19
	v_readlane_b32 s89, v253, 20
	v_readlane_b32 s90, v253, 21
	v_readlane_b32 s91, v253, 22
	global_store_dwordx4 v[6:7], v[2:5], off
	s_cbranch_vccnz .LBB0_699
	s_andn2_b64 vcc, exec, s[20:21]
	s_cbranch_vccnz .LBB0_698
	s_barrier
	s_branch .LBB0_698
